# rotK tab3 + steady-state QK variant with the V transposed reads issued in the a-chain gaps (landed before the barrier)
# speedup vs baseline: 1.0035x; 1.0035x over previous
; __device__ __forceinline__ int crow(int r, int hi) { return (r & 3) + 8 * (r >> 2) + 4 * hi; }
; #define ATT_TR(dst, off) asm volatile("ds_read_b64_tr_b16 %0, %1 offset:%c2" : "=&v"(dst) : "v"(vaddr), "i"(off) : "memory")
; __device__ __forceinline__ float max3f(float a, float b, float c) { float r; asm("v_max3_f32 %0, %1, %2, %3" : "=v"(r) : "v"(a), "v"(b), "v"(c)); return r; }
; #define ATT_TR(dst, off) asm volatile("ds_read_b64_tr_b16 %0, %1 offset:%c2" : "=&v"(dst) : "v"(vaddr), "i"(off) : "memory")
; template <int MODE>
; __device__ __forceinline__ void step64(St& S, const bf16x8 (&qf)[4], int t, int qpos0, bool diag, bool first, float cq, float cfar, const LAS float* tab,
;                                        const LAS unsigned char* buf, unsigned vaddr, int r32, int hi) {
;     ...
;     for (int d0 = 0; d0 < 4; ++d0) { sa = __builtin_amdgcn_mfma_f32_32x32x16_bf16(ka[d0], qf[d0], sa, 0, 0, 0); sb = __builtin_amdgcn_mfma_f32_32x32x16_bf16(kc[d0], qf[d0], sb, 0, 0, 0); }
;     s16x4 vlo[8], vhi[8];
;     ...
;     ATT_TR(vlo[0], 0);           ATT_TR(vhi[0], 1024);          ATT_TR(vlo[1], 2048);        ATT_TR(vhi[1], 3072);
;     ATT_TR(vlo[2], 512);         ATT_TR(vhi[2], 1536);          ATT_TR(vlo[3], 2560);        ATT_TR(vhi[3], 3584);
;     ATT_TR(vlo[4], 4096 + 0);    ATT_TR(vhi[4], 4096 + 1024);   ATT_TR(vlo[5], 4096 + 2048); ATT_TR(vhi[5], 4096 + 3072);
;     ATT_TR(vlo[6], 4096 + 512);  ATT_TR(vhi[6], 4096 + 1536);   ATT_TR(vlo[7], 4096 + 2560); ATT_TR(vhi[7], 4096 + 3584);
;     ...
;     if (MODE == 1 && diag) {
;         const int qrel = qpos0 - t * 64 + r32;
; #pragma unroll
;         for (int r = 0; r < 16; ++r) { if (crow(r, hi) > qrel) sa[r] = -1e30f; if (crow(r, hi) + 32 > qrel) sb[r] = -1e30f; }
;     }
;     float r0 = max3f(sa[0], sa[1], sa[2]), r1 = max3f(sb[0], sb[1], sb[2]);
; #pragma unroll
;     for (int r = 3; r < 15; r += 2) { r0 = max3f(r0, sa[r], sa[r + 1]); r1 = max3f(r1, sb[r], sb[r + 1]); }
;     float rm = max3f(r0, r1, fmaxf(sa[15], sb[15]));
;     rm = xhalf_max(rm);
;     if (first || __any(rm > THR)) {
;         const float dl = first ? rm : fmaxf(rm, 0.f); S.m += dl;
;         const float f = first ? 1.0f : __builtin_amdgcn_exp2f(-dl); S.l *= f;
; #pragma unroll
;         for (int r = 0; r < 16; ++r) { sa[r] -= dl; sb[r] -= dl; S.o0[r] *= f; S.o1[r] *= f; }
;     }
.Lk0_have_init:
	s_cmp_gt_i32 s44, s34
	s_cbranch_scc1 .Lk0_qkP
	s_waitcnt lgkmcnt(7)
	v_mfma_f32_32x32x16_bf16 v[48:63], v[186:189], v[80:83], v[48:63]
	s_waitcnt lgkmcnt(6)
	v_mfma_f32_32x32x16_bf16 v[48:63], v[194:197], v[84:87], v[48:63]
	s_waitcnt lgkmcnt(5)
	v_mfma_f32_32x32x16_bf16 v[48:63], v[202:205], v[88:91], v[48:63]
	s_waitcnt lgkmcnt(4)
	v_mfma_f32_32x32x16_bf16 v[48:63], v[210:213], v[92:95], v[48:63]
	s_waitcnt lgkmcnt(3)
	v_mfma_f32_32x32x16_bf16 v[64:79], v[190:193], v[80:83], v[64:79]
	ds_read_b64_tr_b16 v[112:113], v0
	ds_read_b64_tr_b16 v[114:115], v0 offset:1024
	ds_read_b64_tr_b16 v[104:105], v0 offset:2048
	ds_read_b64_tr_b16 v[106:107], v0 offset:3072
	s_waitcnt lgkmcnt(6)
	v_mfma_f32_32x32x16_bf16 v[64:79], v[198:201], v[84:87], v[64:79]
	ds_read_b64_tr_b16 v[108:109], v0 offset:512
	ds_read_b64_tr_b16 v[110:111], v0 offset:1536
	ds_read_b64_tr_b16 v[100:101], v0 offset:2560
	ds_read_b64_tr_b16 v[102:103], v0 offset:3584
	s_waitcnt lgkmcnt(9)
	v_mfma_f32_32x32x16_bf16 v[64:79], v[206:209], v[88:91], v[64:79]
	ds_read_b64_tr_b16 v[96:97], v0 offset:4096
	ds_read_b64_tr_b16 v[98:99], v0 offset:5120
	ds_read_b64_tr_b16 v[6:7], v0 offset:6144
	ds_read_b64_tr_b16 v[8:9], v0 offset:7168
	s_waitcnt lgkmcnt(12)
	v_mfma_f32_32x32x16_bf16 v[64:79], v[214:217], v[92:95], v[64:79]
	s_waitcnt lgkmcnt(11)
	ds_read_b64_tr_b16 v[10:11], v0 offset:4608
	ds_read_b64_tr_b16 v[12:13], v0 offset:5632
	ds_read_b64_tr_b16 v[2:3], v0 offset:6656
	ds_read_b64_tr_b16 v[4:5], v0 offset:7680
	s_branch .Lk0_qkD
.Lk0_qkP:
	v_mfma_f32_32x32x16_bf16 v[48:63], v[186:189], v[80:83], v[48:63]
	ds_read_b64_tr_b16 v[112:113], v0
	ds_read_b64_tr_b16 v[114:115], v0 offset:1024
	ds_read_b64_tr_b16 v[104:105], v0 offset:2048
	ds_read_b64_tr_b16 v[106:107], v0 offset:3072
	v_mfma_f32_32x32x16_bf16 v[48:63], v[194:197], v[84:87], v[48:63]
	ds_read_b64_tr_b16 v[108:109], v0 offset:512
	ds_read_b64_tr_b16 v[110:111], v0 offset:1536
	ds_read_b64_tr_b16 v[100:101], v0 offset:2560
	ds_read_b64_tr_b16 v[102:103], v0 offset:3584
	v_mfma_f32_32x32x16_bf16 v[48:63], v[202:205], v[88:91], v[48:63]
	ds_read_b64_tr_b16 v[96:97], v0 offset:4096
	ds_read_b64_tr_b16 v[98:99], v0 offset:5120
	ds_read_b64_tr_b16 v[6:7], v0 offset:6144
	ds_read_b64_tr_b16 v[8:9], v0 offset:7168
	v_mfma_f32_32x32x16_bf16 v[48:63], v[210:213], v[92:95], v[48:63]
	s_waitcnt lgkmcnt(11)
	ds_read_b64_tr_b16 v[10:11], v0 offset:4608
	ds_read_b64_tr_b16 v[12:13], v0 offset:5632
	ds_read_b64_tr_b16 v[2:3], v0 offset:6656
	ds_read_b64_tr_b16 v[4:5], v0 offset:7680
	v_mfma_f32_32x32x16_bf16 v[64:79], v[190:193], v[80:83], v[64:79]
	v_mfma_f32_32x32x16_bf16 v[64:79], v[198:201], v[84:87], v[64:79]
	v_mfma_f32_32x32x16_bf16 v[64:79], v[206:209], v[88:91], v[64:79]
	v_mfma_f32_32x32x16_bf16 v[64:79], v[214:217], v[92:95], v[64:79]
.Lk0_qkD:
	s_nop 1
	v_max3_f32 v0, v48, v49, v50
	v_max3_f32 v0, v0, v51, v52
	v_max3_f32 v0, v0, v53, v54
	v_max3_f32 v0, v0, v55, v56
	v_max3_f32 v0, v0, v57, v58
	v_max3_f32 v0, v0, v59, v60
	v_max3_f32 v0, v0, v61, v62
	s_nop 1
	v_max3_f32 v14, v64, v65, v66
	v_max3_f32 v14, v14, v67, v68
	v_max3_f32 v14, v14, v69, v70
	v_max3_f32 v14, v14, v71, v72
	v_max3_f32 v14, v14, v73, v74
	v_max3_f32 v14, v14, v75, v76
	v_max3_f32 v14, v14, v77, v78
	v_max_f32_e32 v15, v63, v79
	v_max3_f32 v0, v0, v14, v15
	s_nop 0
	v_mov_b32_e32 v14, v0
	s_nop 1
	v_permlane32_swap_b32_e32 v0, v14
	v_max_f32_e32 v14, v0, v14
	s_cmp_eq_u32 s44, s34
	s_cbranch_scc1 .Lk0_first
	s_mov_b32 s5, 0x41000000
	v_cmp_lt_f32_e32 vcc, s5, v14
	s_nop 3
	s_cbranch_vccz .Lk0_norescale
	v_max_f32_e32 v0, 0, v14
	v_exp_f32_e64 v14, -v0
	v_add_f32_e32 v157, v157, v0
	v_sub_f32_e32 v48, v48, v0
	v_sub_f32_e32 v49, v49, v0
	v_sub_f32_e32 v50, v50, v0
	v_sub_f32_e32 v51, v51, v0
	v_sub_f32_e32 v52, v52, v0
	v_sub_f32_e32 v53, v53, v0
	v_sub_f32_e32 v54, v54, v0
	v_sub_f32_e32 v55, v55, v0
	v_sub_f32_e32 v56, v56, v0
	v_sub_f32_e32 v57, v57, v0
	v_sub_f32_e32 v58, v58, v0
	v_sub_f32_e32 v59, v59, v0
	v_sub_f32_e32 v60, v60, v0
	v_sub_f32_e32 v61, v61, v0
	v_sub_f32_e32 v62, v62, v0
	v_sub_f32_e32 v63, v63, v0
	v_sub_f32_e32 v64, v64, v0
	v_sub_f32_e32 v65, v65, v0
	v_sub_f32_e32 v66, v66, v0
	v_sub_f32_e32 v67, v67, v0
	v_sub_f32_e32 v68, v68, v0
	v_sub_f32_e32 v69, v69, v0
	v_sub_f32_e32 v70, v70, v0
	v_sub_f32_e32 v71, v71, v0
	v_sub_f32_e32 v72, v72, v0
	v_sub_f32_e32 v73, v73, v0
	v_sub_f32_e32 v74, v74, v0
	v_sub_f32_e32 v75, v75, v0
	v_sub_f32_e32 v76, v76, v0
	v_sub_f32_e32 v77, v77, v0
	v_sub_f32_e32 v78, v78, v0
	v_sub_f32_e32 v79, v79, v0
	v_mul_f32_e32 v150, v150, v14
	v_mul_f32_e32 v16, v16, v14
	v_mul_f32_e32 v17, v17, v14
	v_mul_f32_e32 v18, v18, v14
	v_mul_f32_e32 v19, v19, v14
	v_mul_f32_e32 v20, v20, v14
	v_mul_f32_e32 v21, v21, v14
	v_mul_f32_e32 v22, v22, v14
	v_mul_f32_e32 v23, v23, v14
	v_mul_f32_e32 v24, v24, v14
	v_mul_f32_e32 v25, v25, v14
	v_mul_f32_e32 v26, v26, v14
	v_mul_f32_e32 v27, v27, v14
	v_mul_f32_e32 v28, v28, v14
	v_mul_f32_e32 v29, v29, v14
	v_mul_f32_e32 v30, v30, v14
	v_mul_f32_e32 v31, v31, v14
	v_mul_f32_e32 v32, v32, v14
	v_mul_f32_e32 v33, v33, v14
	v_mul_f32_e32 v34, v34, v14
	v_mul_f32_e32 v35, v35, v14
	v_mul_f32_e32 v36, v36, v14
	v_mul_f32_e32 v37, v37, v14
	v_mul_f32_e32 v38, v38, v14
	v_mul_f32_e32 v39, v39, v14
	v_mul_f32_e32 v40, v40, v14
	v_mul_f32_e32 v41, v41, v14
	v_mul_f32_e32 v42, v42, v14
	v_mul_f32_e32 v43, v43, v14
	v_mul_f32_e32 v44, v44, v14
	v_mul_f32_e32 v45, v45, v14
	v_mul_f32_e32 v46, v46, v14
	v_mul_f32_e32 v47, v47, v14
	s_branch .Lk0_norescale

; #define ATT_TR(dst, off) asm volatile("ds_read_b64_tr_b16 %0, %1 offset:%c2" : "=&v"(dst) : "v"(vaddr), "i"(off) : "memory")
; #define ATT_TR(dst, off) asm volatile("ds_read_b64_tr_b16 %0, %1 offset:%c2" : "=&v"(dst) : "v"(vaddr), "i"(off) : "memory")
; template <int MODE>
; __device__ __forceinline__ void step64(St& S, const bf16x8 (&qf)[4], int t, int qpos0, bool diag, bool first, float cq, float cfar, const LAS float* tab,
;                                        const LAS unsigned char* buf, unsigned vaddr, int r32, int hi) {
;     ...
;     for (int d0 = 0; d0 < 4; ++d0) { sa = __builtin_amdgcn_mfma_f32_32x32x16_bf16(ka[d0], qf[d0], sa, 0, 0, 0); sb = __builtin_amdgcn_mfma_f32_32x32x16_bf16(kc[d0], qf[d0], sb, 0, 0, 0); }
;     s16x4 vlo[8], vhi[8];
;     ...
;     ATT_TR(vlo[0], 0);           ATT_TR(vhi[0], 1024);          ATT_TR(vlo[1], 2048);        ATT_TR(vhi[1], 3072);
;     ATT_TR(vlo[2], 512);         ATT_TR(vhi[2], 1536);          ATT_TR(vlo[3], 2560);        ATT_TR(vhi[3], 3584);
;     ATT_TR(vlo[4], 4096 + 0);    ATT_TR(vhi[4], 4096 + 1024);   ATT_TR(vlo[5], 4096 + 2048); ATT_TR(vhi[5], 4096 + 3072);
;     ATT_TR(vlo[6], 4096 + 512);  ATT_TR(vhi[6], 4096 + 1536);   ATT_TR(vlo[7], 4096 + 2560); ATT_TR(vhi[7], 4096 + 3584);
.Lk1_have_init:
	s_cmp_lt_i32 s22, s28
	s_cbranch_scc1 .Lk1_qkP
	s_waitcnt lgkmcnt(7)
	v_mfma_f32_32x32x16_bf16 v[48:63], v[186:189], v[80:83], v[48:63]
	s_waitcnt lgkmcnt(6)
	v_mfma_f32_32x32x16_bf16 v[48:63], v[194:197], v[84:87], v[48:63]
	s_waitcnt lgkmcnt(5)
	v_mfma_f32_32x32x16_bf16 v[48:63], v[202:205], v[88:91], v[48:63]
	s_waitcnt lgkmcnt(4)
	v_mfma_f32_32x32x16_bf16 v[48:63], v[210:213], v[92:95], v[48:63]
	s_waitcnt lgkmcnt(3)
	v_mfma_f32_32x32x16_bf16 v[64:79], v[190:193], v[80:83], v[64:79]
	ds_read_b64_tr_b16 v[112:113], v0
	ds_read_b64_tr_b16 v[114:115], v0 offset:1024
	ds_read_b64_tr_b16 v[104:105], v0 offset:2048
	ds_read_b64_tr_b16 v[106:107], v0 offset:3072
	s_waitcnt lgkmcnt(6)
	v_mfma_f32_32x32x16_bf16 v[64:79], v[198:201], v[84:87], v[64:79]
	ds_read_b64_tr_b16 v[108:109], v0 offset:512
	ds_read_b64_tr_b16 v[110:111], v0 offset:1536
	ds_read_b64_tr_b16 v[100:101], v0 offset:2560
	ds_read_b64_tr_b16 v[102:103], v0 offset:3584
	s_waitcnt lgkmcnt(9)
	v_mfma_f32_32x32x16_bf16 v[64:79], v[206:209], v[88:91], v[64:79]
	ds_read_b64_tr_b16 v[96:97], v0 offset:4096
	ds_read_b64_tr_b16 v[98:99], v0 offset:5120
	ds_read_b64_tr_b16 v[6:7], v0 offset:6144
	ds_read_b64_tr_b16 v[8:9], v0 offset:7168
	s_waitcnt lgkmcnt(12)
	v_mfma_f32_32x32x16_bf16 v[64:79], v[214:217], v[92:95], v[64:79]
	s_waitcnt lgkmcnt(11)
	ds_read_b64_tr_b16 v[10:11], v0 offset:4608
	ds_read_b64_tr_b16 v[12:13], v0 offset:5632
	ds_read_b64_tr_b16 v[2:3], v0 offset:6656
	ds_read_b64_tr_b16 v[4:5], v0 offset:7680
	s_branch .Lk1_qkD

; __device__ __forceinline__ int crow(int r, int hi) { return (r & 3) + 8 * (r >> 2) + 4 * hi; }
; __device__ __forceinline__ float max3f(float a, float b, float c) { float r; asm("v_max3_f32 %0, %1, %2, %3" : "=v"(r) : "v"(a), "v"(b), "v"(c)); return r; }
; template <int MODE>
; __device__ __forceinline__ void step64(St& S, const bf16x8 (&qf)[4], int t, int qpos0, bool diag, bool first, float cq, float cfar, const LAS float* tab,
;                                        const LAS unsigned char* buf, unsigned vaddr, int r32, int hi) {
;     ...
;     if (MODE == 1 && diag) {
;         const int qrel = qpos0 - t * 64 + r32;
; #pragma unroll
;         for (int r = 0; r < 16; ++r) { if (crow(r, hi) > qrel) sa[r] = -1e30f; if (crow(r, hi) + 32 > qrel) sb[r] = -1e30f; }
;     }
;     float r0 = max3f(sa[0], sa[1], sa[2]), r1 = max3f(sb[0], sb[1], sb[2]);
; #pragma unroll
;     for (int r = 3; r < 15; r += 2) { r0 = max3f(r0, sa[r], sa[r + 1]); r1 = max3f(r1, sb[r], sb[r + 1]); }
;     float rm = max3f(r0, r1, fmaxf(sa[15], sb[15]));
;     rm = xhalf_max(rm);
.Lk1_qkD:
	s_cmp_lg_u32 s4, 1
	s_cbranch_scc1 .Lk1_nodiag
	s_nop 7
	s_nop 3
	v_cndmask_b32_e64 v0, v48, v140, s[34:35]
	s_nop 0
	v_cndmask_b32_e64 v64, v64, v140, s[36:37]
	v_cndmask_b32_e64 v49, v140, v49, s[38:39]
	v_cndmask_b32_e64 v48, v0, v48, s[38:39]
	v_cndmask_b32_e64 v65, v65, v140, s[40:41]
	v_cndmask_b32_e64 v50, v50, v140, s[42:43]
	v_cndmask_b32_e64 v66, v66, v140, s[44:45]
	v_cndmask_b32_e64 v51, v51, v140, s[46:47]
	v_cndmask_b32_e64 v67, v67, v140, s[48:49]
	v_cndmask_b32_e64 v52, v52, v140, s[50:51]
	v_cndmask_b32_e64 v68, v68, v140, s[52:53]
	v_cndmask_b32_e64 v53, v53, v140, s[54:55]
	v_cndmask_b32_e64 v69, v69, v140, s[56:57]
	v_cndmask_b32_e64 v54, v54, v140, s[58:59]
	v_cndmask_b32_e64 v70, v70, v140, s[60:61]
	v_cndmask_b32_e64 v55, v55, v140, s[62:63]
	v_cndmask_b32_e64 v71, v71, v140, s[64:65]
	v_cndmask_b32_e64 v56, v56, v140, s[66:67]
	v_cndmask_b32_e64 v72, v72, v140, s[68:69]
	v_cndmask_b32_e64 v57, v57, v140, s[70:71]
	v_cndmask_b32_e64 v73, v73, v140, s[72:73]
	v_cndmask_b32_e64 v58, v58, v140, s[74:75]
	v_cndmask_b32_e64 v74, v74, v140, s[76:77]
	v_cndmask_b32_e64 v59, v59, v140, s[78:79]
	v_cndmask_b32_e64 v75, v75, v140, s[80:81]
	v_cndmask_b32_e64 v60, v60, v140, s[82:83]
	v_cndmask_b32_e64 v76, v76, v140, s[84:85]
	v_cndmask_b32_e64 v61, v61, v140, s[86:87]
	v_cndmask_b32_e64 v77, v77, v140, s[88:89]
	v_cndmask_b32_e64 v62, v62, v140, s[90:91]
	v_cndmask_b32_e64 v78, v78, v140, s[92:93]
	v_cndmask_b32_e64 v63, v63, v140, s[94:95]
	v_cndmask_b32_e64 v79, v79, v140, s[96:97]
